# v23 + attention softmax: exp2 argument as one v_fmamk_f32 (x*log2e - m*log2e) instead of v_sub + v_mul (36 fewer VALU per query subtile; f32 fused multiply-add)
# speedup vs baseline: 1.0039x; 1.0025x over previous
; __device__ __forceinline__ unsigned pk2(float lo, float hi) { f32x2_t v = {lo, hi}; bf16x2_t b = __builtin_convertvector(v, bf16x2_t); return __builtin_bit_cast(unsigned, b); }
; #define LDS_WAIT() asm volatile("s_waitcnt lgkmcnt(0)" ::: "memory")
; __device__ __forceinline__ void attn_unit(const AtArgs& A, unsigned char* lds, int unit, int tid, int wave, int lane) {
;     ...
;         const int q0 = qh * 64 + st * 16;
;         {
;             const int row = lane >> 2, chunk = lane & 3;
;             const size_t t = (size_t)b * SEQ + nb * 128 + q0 + row;
;             float x[16];
;             const u32x4 qc0 = qn0, qc1 = qn1;
;             { const bf16* pn = pq0 + (size_t)((st < 3) ? st + 1 : 3) * 16 * QW; qn0 = *(const u32x4*)pn; qn1 = *(const u32x4*)(pn + 8); }
;             norm_rope(qc0, qc1, A.qg, chunk, ROPE + t * 16, 0.125f, x);
;             u32x4 o0, o1; o0.x = pk2(x[0], x[1]); o0.y = pk2(x[2], x[3]); o0.z = pk2(x[4], x[5]); o0.w = pk2(x[6], x[7]); o1.x = pk2(x[8], x[9]); o1.y = pk2(x[10], x[11]); o1.z = pk2(x[12], x[13]); o1.w = pk2(x[14], x[15]);
;             *(u32x4*)(QS + row * QST + chunk * 16) = o0; *(u32x4*)(QS + row * QST + chunk * 16 + 8) = o1;
;         }
;         LDS_WAIT();
;         const bf16x8 qa0 = *(const bf16x8*)(QS + fr * QST + fq * 8), qa1 = *(const bf16x8*)(QS + fr * QST + 32 + fq * 8);
;         f32x4 sc[9];
; #pragma unroll
;         for (int kt = 0; kt < 9; ++kt) {
;             const int key = (q0 / 16 + kt) * 16 + fr;
;             const bf16x8 kb0 = *(const bf16x8*)(KS + key * KST + fq * 8), kb1 = *(const bf16x8*)(KS + key * KST + 32 + fq * 8);
;             f32x4 a = (f32x4){0.f, 0.f, 0.f, 0.f};
;             a = __builtin_amdgcn_mfma_f32_16x16x32_bf16(qa0, kb0, a, 0, 0, 0); a = __builtin_amdgcn_mfma_f32_16x16x32_bf16(qa1, kb1, a, 0, 0, 0);
; #pragma unroll
;             for (int r = 0; r < 4; ++r) {
;                 const int qi = q0 + fq * 4 + r;
;                 const bool ok = (key > qi) && (key <= qi + 128) && (nb > 0 || key >= 128);
;                 a[r] = ok ? a[r] : -1e30f;
;             }
;             sc[kt] = a;
;         }
.LBB0_510:
	s_or_b64 exec, exec, s[0:1]
	v_pk_mul_f32 v[18:19], v[60:61], s[14:15] op_sel_hi:[1,0]
	v_pk_mul_f32 v[20:21], v[28:29], s[14:15] op_sel_hi:[1,0]
	v_pk_mul_f32 v[22:23], v[24:25], s[14:15] op_sel_hi:[1,0]
	v_pk_mul_f32 v[12:13], v[12:13], s[14:15] op_sel_hi:[1,0]
	v_pk_mul_f32 v[24:25], v[8:9], s[14:15] op_sel_hi:[1,0]
	v_pk_mul_f32 v[26:27], v[10:11], s[14:15] op_sel_hi:[1,0]
	v_pk_mul_f32 v[14:15], v[14:15], s[14:15] op_sel_hi:[1,0]
	v_pk_mul_f32 v[16:17], v[16:17], s[14:15] op_sel_hi:[1,0]
	v_cvt_pk_bf16_f32 v8, v18, v19
	v_cvt_pk_bf16_f32 v9, v20, v21
	v_cvt_pk_bf16_f32 v10, v22, v23
	v_cvt_pk_bf16_f32 v11, v12, v13
	v_cvt_pk_bf16_f32 v12, v24, v25
	v_cvt_pk_bf16_f32 v13, v26, v27
	v_cvt_pk_bf16_f32 v14, v14, v15
	v_cvt_pk_bf16_f32 v15, v16, v17
	ds_write_b128 v75, v[8:11]
	ds_write_b128 v75, v[12:15] offset:16
	s_waitcnt lgkmcnt(0)
	ds_read_b128 v[12:15], v76
	ds_read_b128 v[8:11], v76 offset:64
	ds_read_b128 v[16:19], v95
	ds_read_b128 v[20:23], v95 offset:64
	s_waitcnt lgkmcnt(1)
	v_mfma_f32_16x16x32_bf16 v[16:19], v[12:15], v[16:19], 0
	v_add_u32_e32 v30, s2, v85
	v_add_u32_e32 v31, s2, v88
	v_add_u32_e32 v58, 1, v31
	s_waitcnt lgkmcnt(0)
	v_mfma_f32_16x16x32_bf16 v[16:19], v[8:11], v[20:23], v[16:19]
	v_add_u32_e32 v20, 0xffffff80, v30
	v_cmp_ge_i32_e32 vcc, v31, v20
	s_and_b64 s[0:1], s[42:43], vcc
	s_and_b64 vcc, s[16:17], s[0:1]
	v_cmp_ge_i32_e64 s[0:1], v58, v20
	s_nop 2
	v_cndmask_b32_e32 v29, v93, v16, vcc
	v_cmp_gt_i32_e32 vcc, v30, v58
	s_and_b64 s[0:1], vcc, s[0:1]
	s_and_b64 vcc, s[16:17], s[0:1]
	v_add_u32_e32 v59, 2, v31
	ds_read_b128 v[96:99], v95 offset:2304
	ds_read_b128 v[100:103], v95 offset:2368
	v_cndmask_b32_e32 v22, v93, v17, vcc
	v_cmp_gt_i32_e32 vcc, v30, v59
	v_cmp_ge_i32_e64 s[0:1], v59, v20
	s_and_b64 s[0:1], vcc, s[0:1]
	s_and_b64 vcc, s[16:17], s[0:1]
	v_add_u32_e32 v60, 3, v31
	v_cndmask_b32_e32 v18, v93, v18, vcc
	v_cmp_gt_i32_e32 vcc, v30, v60
	v_cmp_ge_i32_e64 s[0:1], v60, v20
	s_waitcnt lgkmcnt(1)
	v_mfma_f32_16x16x32_bf16 v[96:99], v[12:15], v[96:99], 0
	s_and_b64 s[0:1], vcc, s[0:1]
	s_add_i32 s6, s4, s2
	s_and_b64 vcc, s[16:17], s[0:1]
	s_add_i32 s0, s6, 16
	s_cmpk_gt_u32 s0, 0x7f
	v_cndmask_b32_e32 v16, v93, v19, vcc
	v_add_u32_e32 v17, 16, v30
	s_waitcnt lgkmcnt(0)
	v_mfma_f32_16x16x32_bf16 v[96:99], v[8:11], v[100:103], v[96:99]
	v_add_u32_e32 v19, 0xffffff90, v30
	s_cselect_b64 s[0:1], -1, 0
	s_or_b64 s[10:11], s[16:17], s[0:1]
	v_cmp_gt_i32_e32 vcc, v17, v31
	v_cmp_ge_i32_e64 s[0:1], v31, v19
	s_and_b64 s[0:1], vcc, s[0:1]
	s_and_b64 vcc, s[0:1], s[10:11]
	s_nop 0
	v_cndmask_b32_e32 v96, v93, v96, vcc
	v_cmp_gt_i32_e32 vcc, v17, v58
	v_cmp_ge_i32_e64 s[0:1], v58, v19
	s_and_b64 s[0:1], vcc, s[0:1]
	s_and_b64 vcc, s[0:1], s[10:11]
	v_cndmask_b32_e32 v26, v93, v97, vcc
	v_cmp_gt_i32_e32 vcc, v17, v59
	v_cmp_ge_i32_e64 s[0:1], v59, v19
	s_and_b64 s[0:1], vcc, s[0:1]
	s_and_b64 vcc, s[0:1], s[10:11]
	v_cndmask_b32_e32 v20, v93, v98, vcc
	v_cmp_gt_i32_e32 vcc, v17, v60
	v_cmp_ge_i32_e64 s[0:1], v60, v19
	s_and_b64 s[0:1], vcc, s[0:1]
	s_and_b64 vcc, s[0:1], s[10:11]
	v_cndmask_b32_e32 v17, v93, v99, vcc
	ds_read_b128 v[98:101], v95 offset:4608
	ds_read_b128 v[108:111], v95 offset:4672
	s_waitcnt lgkmcnt(1)
	v_mfma_f32_16x16x32_bf16 v[98:101], v[12:15], v[98:101], 0
	s_add_i32 s0, s6, 32
	s_cmpk_gt_u32 s0, 0x7f
	v_add_u32_e32 v19, 32, v30
	s_waitcnt lgkmcnt(0)
	v_mfma_f32_16x16x32_bf16 v[100:103], v[8:11], v[108:111], v[98:101]
	v_add_u32_e32 v21, 0xffffffa0, v30
	s_cselect_b64 s[0:1], -1, 0
	s_or_b64 s[10:11], s[16:17], s[0:1]
	v_cmp_gt_i32_e32 vcc, v19, v31
	v_cmp_ge_i32_e64 s[0:1], v31, v21
	s_and_b64 s[0:1], vcc, s[0:1]
	s_and_b64 vcc, s[0:1], s[10:11]
	s_nop 0
	v_cndmask_b32_e32 v100, v93, v100, vcc
	v_cmp_gt_i32_e32 vcc, v19, v58
	v_cmp_ge_i32_e64 s[0:1], v58, v21
	s_and_b64 s[0:1], vcc, s[0:1]
	s_and_b64 vcc, s[0:1], s[10:11]
	ds_read_b128 v[108:111], v95 offset:6912
	ds_read_b128 v[112:115], v95 offset:6976
	v_cndmask_b32_e32 v56, v93, v101, vcc
	v_cmp_gt_i32_e32 vcc, v19, v59
	v_cmp_ge_i32_e64 s[0:1], v59, v21
	s_and_b64 s[0:1], vcc, s[0:1]
	s_and_b64 vcc, s[0:1], s[10:11]
	v_cndmask_b32_e32 v23, v93, v102, vcc
	v_cmp_gt_i32_e32 vcc, v19, v60
	v_cmp_ge_i32_e64 s[0:1], v60, v21
	s_waitcnt lgkmcnt(1)
	v_mfma_f32_16x16x32_bf16 v[108:111], v[12:15], v[108:111], 0
	s_and_b64 s[0:1], vcc, s[0:1]
	s_and_b64 vcc, s[0:1], s[10:11]
	s_add_i32 s0, s6, 48
	s_cmpk_gt_u32 s0, 0x7f
	v_add_u32_e32 v21, 48, v30
	s_waitcnt lgkmcnt(0)
	v_mfma_f32_16x16x32_bf16 v[108:111], v[8:11], v[112:115], v[108:111]
	v_add_u32_e32 v25, 0xffffffb0, v30
	s_cselect_b64 s[0:1], -1, 0
	v_cndmask_b32_e32 v19, v93, v103, vcc
	s_or_b64 s[10:11], s[16:17], s[0:1]
	v_cmp_gt_i32_e32 vcc, v21, v31
	v_cmp_ge_i32_e64 s[0:1], v31, v25
	s_and_b64 s[0:1], vcc, s[0:1]
	s_and_b64 vcc, s[0:1], s[10:11]
	v_cndmask_b32_e32 v103, v93, v108, vcc
	v_cmp_gt_i32_e32 vcc, v21, v58
	v_cmp_ge_i32_e64 s[0:1], v58, v25
	s_and_b64 s[0:1], vcc, s[0:1]
	s_and_b64 vcc, s[0:1], s[10:11]
	v_cndmask_b32_e32 v97, v93, v109, vcc
	v_cmp_gt_i32_e32 vcc, v21, v59
	v_cmp_ge_i32_e64 s[0:1], v59, v25
	s_and_b64 s[0:1], vcc, s[0:1]
	s_and_b64 vcc, s[0:1], s[10:11]
	v_cndmask_b32_e32 v27, v93, v110, vcc
	v_cmp_gt_i32_e32 vcc, v21, v60
	v_cmp_ge_i32_e64 s[0:1], v60, v25
	s_and_b64 s[0:1], vcc, s[0:1]
	s_and_b64 vcc, s[0:1], s[10:11]
	v_cndmask_b32_e32 v21, v93, v111, vcc
	ds_read_b128 v[108:111], v95 offset:9216
	ds_read_b128 v[112:115], v95 offset:9280
	s_waitcnt lgkmcnt(1)
	v_mfma_f32_16x16x32_bf16 v[108:111], v[12:15], v[108:111], 0
	s_add_i32 s0, s6, 64
	s_cmpk_gt_u32 s0, 0x7f
	v_add_u32_e32 v25, 64, v30
	s_waitcnt lgkmcnt(0)
; __device__ __forceinline__ void attn_unit(const AtArgs& A, unsigned char* lds, int unit, int tid, int wave, int lane) {
;     ...
;         for (int kt = 0; kt < 9; ++kt) {
;             const int key = (q0 / 16 + kt) * 16 + fr;
;             const bf16x8 kb0 = *(const bf16x8*)(KS + key * KST + fq * 8), kb1 = *(const bf16x8*)(KS + key * KST + 32 + fq * 8);
;             f32x4 a = (f32x4){0.f, 0.f, 0.f, 0.f};
;             a = __builtin_amdgcn_mfma_f32_16x16x32_bf16(qa0, kb0, a, 0, 0, 0); a = __builtin_amdgcn_mfma_f32_16x16x32_bf16(qa1, kb1, a, 0, 0, 0);
; #pragma unroll
;             for (int r = 0; r < 4; ++r) {
;                 const int qi = q0 + fq * 4 + r;
;                 const bool ok = (key > qi) && (key <= qi + 128) && (nb > 0 || key >= 128);
;                 a[r] = ok ? a[r] : -1e30f;
;             }
;             sc[kt] = a;
;         }
	v_mfma_f32_16x16x32_bf16 v[108:111], v[8:11], v[112:115], v[108:111]
	v_subrev_u32_e32 v28, 64, v30
	s_cselect_b64 s[0:1], -1, 0
	s_or_b64 s[10:11], s[16:17], s[0:1]
	v_cmp_gt_i32_e32 vcc, v25, v31
	v_cmp_ge_i32_e64 s[0:1], v31, v28
	s_and_b64 s[0:1], vcc, s[0:1]
	s_and_b64 vcc, s[0:1], s[10:11]
	s_nop 0
	v_cndmask_b32_e32 v116, v93, v108, vcc
	v_cmp_gt_i32_e32 vcc, v25, v58
	v_cmp_ge_i32_e64 s[0:1], v58, v28
	s_and_b64 s[0:1], vcc, s[0:1]
	s_and_b64 vcc, s[0:1], s[10:11]
	v_cndmask_b32_e32 v101, v93, v109, vcc
	v_cmp_gt_i32_e32 vcc, v25, v59
	v_cmp_ge_i32_e64 s[0:1], v59, v28
	s_and_b64 s[0:1], vcc, s[0:1]
	s_and_b64 vcc, s[0:1], s[10:11]
	v_cndmask_b32_e32 v57, v93, v110, vcc
	v_cmp_gt_i32_e32 vcc, v25, v60
	v_cmp_ge_i32_e64 s[0:1], v60, v28
	s_and_b64 s[0:1], vcc, s[0:1]
	s_and_b64 vcc, s[0:1], s[10:11]
	v_cndmask_b32_e32 v25, v93, v111, vcc
	ds_read_b128 v[108:111], v95 offset:11520
	ds_read_b128 v[112:115], v95 offset:11584
	s_waitcnt lgkmcnt(1)
	v_mfma_f32_16x16x32_bf16 v[108:111], v[12:15], v[108:111], 0
	s_add_i32 s0, s6, 0x50
	s_cmpk_gt_u32 s0, 0x7f
	v_add_u32_e32 v28, 0x50, v30
	s_waitcnt lgkmcnt(0)
	v_mfma_f32_16x16x32_bf16 v[108:111], v[8:11], v[112:115], v[108:111]
	v_subrev_u32_e32 v61, 48, v30
	s_cselect_b64 s[0:1], -1, 0
	s_or_b64 s[10:11], s[16:17], s[0:1]
	v_cmp_gt_i32_e32 vcc, v28, v31
	v_cmp_ge_i32_e64 s[0:1], v31, v61
	s_and_b64 s[0:1], vcc, s[0:1]
	s_and_b64 vcc, s[0:1], s[10:11]
	s_nop 0
	v_cndmask_b32_e32 v117, v93, v108, vcc
	v_cmp_gt_i32_e32 vcc, v28, v58
	v_cmp_ge_i32_e64 s[0:1], v58, v61
	s_and_b64 s[0:1], vcc, s[0:1]
	s_and_b64 vcc, s[0:1], s[10:11]
	v_cndmask_b32_e32 v118, v93, v109, vcc
	v_cmp_gt_i32_e32 vcc, v28, v59
	v_cmp_ge_i32_e64 s[0:1], v59, v61
	s_and_b64 s[0:1], vcc, s[0:1]
	s_and_b64 vcc, s[0:1], s[10:11]
	v_cndmask_b32_e32 v98, v93, v110, vcc
	v_cmp_gt_i32_e32 vcc, v28, v60
	v_cmp_ge_i32_e64 s[0:1], v60, v61
	s_and_b64 s[0:1], vcc, s[0:1]
	s_and_b64 vcc, s[0:1], s[10:11]
	v_cndmask_b32_e32 v28, v93, v111, vcc
	ds_read_b128 v[108:111], v95 offset:13824
	ds_read_b128 v[112:115], v95 offset:13888
	s_waitcnt lgkmcnt(1)
	v_mfma_f32_16x16x32_bf16 v[108:111], v[12:15], v[108:111], 0
	s_add_i32 s0, s6, 0x60
	s_cmpk_gt_u32 s0, 0x7f
	v_add_u32_e32 v61, 0x60, v30
	s_waitcnt lgkmcnt(0)
	v_mfma_f32_16x16x32_bf16 v[108:111], v[8:11], v[112:115], v[108:111]
	v_subrev_u32_e32 v99, 32, v30
	s_cselect_b64 s[0:1], -1, 0
	s_or_b64 s[10:11], s[16:17], s[0:1]
	v_cmp_gt_i32_e32 vcc, v61, v31
	v_cmp_ge_i32_e64 s[0:1], v31, v99
	s_and_b64 s[0:1], vcc, s[0:1]
	s_and_b64 vcc, s[0:1], s[10:11]
	s_nop 0
	v_cndmask_b32_e32 v119, v93, v108, vcc
	v_cmp_gt_i32_e32 vcc, v61, v58
	v_cmp_ge_i32_e64 s[0:1], v58, v99
	s_and_b64 s[0:1], vcc, s[0:1]
	s_and_b64 vcc, s[0:1], s[10:11]
	v_cndmask_b32_e32 v120, v93, v109, vcc
	v_cmp_gt_i32_e32 vcc, v61, v59
	v_cmp_ge_i32_e64 s[0:1], v59, v99
	s_and_b64 s[0:1], vcc, s[0:1]
	s_and_b64 vcc, s[0:1], s[10:11]
	v_cndmask_b32_e32 v102, v93, v110, vcc
	v_cmp_gt_i32_e32 vcc, v61, v60
	v_cmp_ge_i32_e64 s[0:1], v60, v99
	s_and_b64 s[0:1], vcc, s[0:1]
	s_and_b64 vcc, s[0:1], s[10:11]
	v_cndmask_b32_e32 v61, v93, v111, vcc
	ds_read_b128 v[108:111], v95 offset:16128
	ds_read_b128 v[112:115], v95 offset:16192
	s_waitcnt lgkmcnt(1)
	v_mfma_f32_16x16x32_bf16 v[108:111], v[12:15], v[108:111], 0
	s_addk_i32 s6, 0x70
	s_cmpk_gt_u32 s6, 0x7f
	v_add_u32_e32 v99, 0x70, v30
	s_waitcnt lgkmcnt(0)
	v_mfma_f32_16x16x32_bf16 v[108:111], v[8:11], v[112:115], v[108:111]
	v_add_u32_e32 v112, -16, v30
	s_cselect_b64 s[0:1], -1, 0
	s_or_b64 s[10:11], s[16:17], s[0:1]
	v_cmp_gt_i32_e32 vcc, v99, v31
	v_cmp_ge_i32_e64 s[0:1], v31, v112
	s_and_b64 s[0:1], vcc, s[0:1]
	s_and_b64 vcc, s[0:1], s[10:11]
	s_nop 0
	v_cndmask_b32_e32 v121, v93, v108, vcc
	v_cmp_gt_i32_e32 vcc, v99, v58
	v_cmp_ge_i32_e64 s[0:1], v58, v112
	s_and_b64 s[0:1], vcc, s[0:1]
	s_and_b64 vcc, s[0:1], s[10:11]
	v_cndmask_b32_e32 v122, v93, v109, vcc
	v_cmp_gt_i32_e32 vcc, v99, v59
	v_cmp_ge_i32_e64 s[0:1], v59, v112
	s_and_b64 s[0:1], vcc, s[0:1]
	s_and_b64 vcc, s[0:1], s[10:11]
	v_cndmask_b32_e32 v123, v93, v110, vcc
	v_cmp_gt_i32_e32 vcc, v99, v60
	v_cmp_ge_i32_e64 s[0:1], v60, v112
	s_and_b64 s[0:1], vcc, s[0:1]
	s_and_b64 vcc, s[0:1], s[10:11]
	v_cndmask_b32_e32 v99, v93, v111, vcc
	ds_read_b128 v[108:111], v95 offset:18432
	ds_read_b128 v[112:115], v95 offset:18496
	s_waitcnt lgkmcnt(1)
	v_mfma_f32_16x16x32_bf16 v[12:15], v[12:15], v[108:111], 0
	v_add_u32_e32 v124, 0x80, v30
	v_cmp_gt_i32_e32 vcc, v124, v31
	v_cmp_ge_i32_e64 s[0:1], v31, v30
	s_waitcnt lgkmcnt(0)
; __device__ __forceinline__ float row16_sum(float v) { v += dpp_perm<0xB1, 0xF>(v); v += dpp_perm<0x4E, 0xF>(v); v += dpp_perm<0x141, 0xF>(v); v += dpp_perm<0x140, 0xF>(v); return v; }
; __device__ __forceinline__ float row16_max(float v) { v = fmaxf(v, dpp_perm<0xB1, 0xF>(v)); v = fmaxf(v, dpp_perm<0x4E, 0xF>(v)); v = fmaxf(v, dpp_perm<0x141, 0xF>(v)); v = fmaxf(v, dpp_perm<0x140, 0xF>(v)); return v; }
; __device__ __forceinline__ void attn_unit(const AtArgs& A, unsigned char* lds, int unit, int tid, int wave, int lane) {
;     ...
;         float m4[4], s4[4];
; #pragma unroll
;         for (int r = 0; r < 4; ++r) {
;             float m = sc[0][r];
; #pragma unroll
;             for (int kt = 1; kt < 9; ++kt) m = fmaxf(m, sc[kt][r]);
;             m = row16_max(m);
;             m4[r] = fmaxf(m, sink);
;             float s = 0.f;
; #pragma unroll
;             for (int kt = 0; kt < 9; ++kt) { const float e = __expf(sc[kt][r] - m4[r]); sc[kt][r] = e; s += e; }
;             s = row16_sum(s);
;             s4[r] = __builtin_amdgcn_rcpf(s + __expf(sink - m4[r]));
;         }
	v_mfma_f32_16x16x32_bf16 v[8:11], v[8:11], v[112:115], v[12:15]
	s_and_b64 vcc, vcc, s[0:1]
	v_cmp_ge_i32_e64 s[0:1], v58, v30
	v_add_u32_e32 v24, 0x900, v95
	v_mov_b32_e32 v95, 0
	v_mov_b32_e32 v108, 0
	s_nop 2
	v_cndmask_b32_e32 v8, v93, v8, vcc
	v_cmp_gt_i32_e32 vcc, v124, v58
	s_and_b64 vcc, vcc, s[0:1]
	v_cmp_ge_i32_e64 s[0:1], v59, v30
	v_cndmask_b32_e32 v58, v93, v9, vcc
	v_max3_f32 v9, v29, v96, v100
	v_cmp_gt_i32_e32 vcc, v124, v59
	v_max3_f32 v9, v9, v103, v116
	s_and_b64 vcc, vcc, s[0:1]
	v_max3_f32 v9, v9, v117, v119
	v_cndmask_b32_e32 v59, v93, v10, vcc
	v_max3_f32 v9, v9, v121, v8
	v_mov_b32_e32 v10, 0
	v_cmp_ge_i32_e64 s[0:1], v60, v30
	v_cmp_gt_i32_e32 vcc, v124, v60
	v_mov_b32_dpp v10, v9 quad_perm:[1,0,3,2] row_mask:0xf bank_mask:0xf
	v_max_f32_e32 v10, v10, v10
	v_max_f32_e32 v9, v9, v10
	v_mov_b32_e32 v10, 0
	s_and_b64 vcc, vcc, s[0:1]
	v_cndmask_b32_e32 v31, v93, v11, vcc
	v_mov_b32_dpp v10, v9 quad_perm:[2,3,0,1] row_mask:0xf bank_mask:0xf
	v_max_f32_e32 v10, v10, v10
	v_max_f32_e32 v9, v9, v10
	v_mov_b32_e32 v10, 0
	v_mov_b32_e32 v110, 0
	s_add_i32 s2, s2, 16
	v_mov_b32_dpp v10, v9 row_half_mirror row_mask:0xf bank_mask:0xf
	v_max_f32_e32 v10, v10, v10
	v_max_f32_e32 v9, v9, v10
	v_mov_b32_e32 v10, 0
	s_add_i32 s3, s3, 0xb000
	s_nop 0
	v_mov_b32_dpp v10, v9 row_mirror row_mask:0xf bank_mask:0xf
	v_max3_f32 v30, v9, v10, v38
	v_mul_f32_e32 v144, 0xbfb8aa3b, v30
	v_fmamk_f32 v10, v96, 0x3fb8aa3b, v144
	s_nop 0
	v_fmamk_f32 v9, v29, 0x3fb8aa3b, v144
	v_exp_f32_e32 v29, v10
	v_fmamk_f32 v10, v100, 0x3fb8aa3b, v144
	s_nop 0
	s_nop 0
	v_exp_f32_e32 v14, v9
	v_exp_f32_e32 v15, v10
	v_fmamk_f32 v10, v103, 0x3fb8aa3b, v144
	s_nop 0
	v_exp_f32_e32 v12, v10
	v_fmamk_f32 v10, v116, 0x3fb8aa3b, v144
	v_fmamk_f32 v11, v117, 0x3fb8aa3b, v144
	s_nop 0
	s_nop 0
	v_add_f32_e32 v9, 0, v14
	v_exp_f32_e32 v10, v10
	v_exp_f32_e32 v13, v11
	v_fmamk_f32 v11, v119, 0x3fb8aa3b, v144
	v_add_f32_e32 v9, v29, v9
	s_nop 0
	v_add_f32_e32 v9, v15, v9
	v_exp_f32_e32 v11, v11
	v_add_f32_e32 v9, v12, v9
	v_add_f32_e32 v9, v10, v9
	v_add_f32_e32 v9, v13, v9
	v_add_f32_e32 v60, v11, v9
	v_fmamk_f32 v9, v121, 0x3fb8aa3b, v144
	s_nop 0
	v_fmamk_f32 v8, v8, 0x3fb8aa3b, v144
	v_exp_f32_e32 v9, v9
	s_nop 0
	v_exp_f32_e32 v8, v8
	v_fmamk_f32 v30, v38, 0x3fb8aa3b, v144
	v_add_f32_e32 v60, v9, v60
	s_nop 0
	v_add_f32_e32 v60, v8, v60
	v_exp_f32_e32 v30, v30
	s_nop 0
	v_add_f32_dpp v60, v60, v60 quad_perm:[1,0,3,2] row_mask:0xf bank_mask:0xf bound_ctrl:1
	s_nop 1
	v_add_f32_dpp v60, v60, v60 quad_perm:[2,3,0,1] row_mask:0xf bank_mask:0xf bound_ctrl:1
	s_nop 1
	v_add_f32_dpp v60, v60, v60 row_half_mirror row_mask:0xf bank_mask:0xf bound_ctrl:1
	s_nop 1
	v_add_f32_dpp v60, v60, v60 row_mirror row_mask:0xf bank_mask:0xf bound_ctrl:1
	v_add_f32_e32 v30, v30, v60
	v_max3_f32 v60, v22, v26, v56
	v_max3_f32 v60, v60, v97, v101
	v_max3_f32 v60, v60, v118, v120
	v_max3_f32 v60, v60, v122, v58
	v_rcp_f32_e32 v30, v30
	s_nop 0
	v_mov_b32_dpp v95, v60 quad_perm:[1,0,3,2] row_mask:0xf bank_mask:0xf
	v_max_f32_e32 v95, v95, v95
	v_max_f32_e32 v60, v60, v95
	v_mov_b32_e32 v95, 0
	v_mul_f32_e32 v14, v14, v30
	v_mul_f32_e32 v10, v10, v30
	v_mov_b32_dpp v95, v60 quad_perm:[2,3,0,1] row_mask:0xf bank_mask:0xf
	v_max_f32_e32 v95, v95, v95
	v_max_f32_e32 v60, v60, v95
	v_mov_b32_e32 v95, 0
	v_cvt_pk_bf16_f32 v14, v14, s0
	v_cvt_pk_bf16_f32 v10, v10, s0
	v_mov_b32_dpp v95, v60 row_half_mirror row_mask:0xf bank_mask:0xf
	v_max_f32_e32 v95, v95, v95
	v_max_f32_e32 v60, v60, v95
	v_mov_b32_e32 v95, 0
	ds_write_b16 v79, v14
	ds_write_b16 v79, v10 offset:128
	v_mov_b32_dpp v95, v60 row_mirror row_mask:0xf bank_mask:0xf
	v_max3_f32 v60, v60, v95, v38
	v_mul_f32_e32 v145, 0xbfb8aa3b, v60
	v_fmamk_f32 v22, v22, 0x3fb8aa3b, v145
	s_nop 0
	v_fmamk_f32 v26, v26, 0x3fb8aa3b, v145
	v_exp_f32_e32 v22, v22
	s_nop 0
	v_fmamk_f32 v56, v56, 0x3fb8aa3b, v145
	v_exp_f32_e32 v26, v26
	s_nop 0
	v_fmamk_f32 v96, v97, 0x3fb8aa3b, v145
	v_exp_f32_e32 v56, v56
	s_nop 0
	v_fmamk_f32 v97, v101, 0x3fb8aa3b, v145
	v_exp_f32_e32 v96, v96
	s_nop 0
	v_fmamk_f32 v100, v118, 0x3fb8aa3b, v145
	v_add_f32_e32 v95, 0, v22
	v_exp_f32_e32 v97, v97
	s_nop 0
	v_fmamk_f32 v101, v120, 0x3fb8aa3b, v145
	v_add_f32_e32 v95, v26, v95
	v_exp_f32_e32 v100, v100
	s_nop 0
	v_fmamk_f32 v103, v122, 0x3fb8aa3b, v145
	v_add_f32_e32 v95, v56, v95
	v_exp_f32_e32 v101, v101
	s_nop 0
	v_fmamk_f32 v58, v58, 0x3fb8aa3b, v145
	v_add_f32_e32 v95, v96, v95
	v_exp_f32_e32 v103, v103
	s_nop 0
	v_add_f32_e32 v95, v97, v95
	v_exp_f32_e32 v58, v58
	v_add_f32_e32 v95, v100, v95
	v_add_f32_e32 v95, v101, v95
	v_add_f32_e32 v95, v103, v95
	v_fmamk_f32 v60, v38, 0x3fb8aa3b, v145
	v_add_f32_e32 v95, v58, v95
	s_nop 0
	v_exp_f32_e32 v60, v60
	v_add_f32_dpp v95, v95, v95 quad_perm:[1,0,3,2] row_mask:0xf bank_mask:0xf bound_ctrl:1
	v_mul_f32_e32 v12, v12, v30
	v_mul_f32_e32 v9, v9, v30
	v_add_f32_dpp v95, v95, v95 quad_perm:[2,3,0,1] row_mask:0xf bank_mask:0xf bound_ctrl:1
	v_mul_f32_e32 v8, v8, v30
	v_cvt_pk_bf16_f32 v12, v12, s0
	v_add_f32_dpp v95, v95, v95 row_half_mirror row_mask:0xf bank_mask:0xf bound_ctrl:1
	v_cvt_pk_bf16_f32 v9, v9, s0
	v_cvt_pk_bf16_f32 v8, v8, s0
	v_add_f32_dpp v95, v95, v95 row_mirror row_mask:0xf bank_mask:0xf bound_ctrl:1
	v_add_f32_e32 v60, v60, v95
	v_max3_f32 v95, v18, v20, v23
	v_max3_f32 v95, v95, v27, v57
	v_max3_f32 v95, v95, v98, v102
	v_max3_f32 v95, v95, v123, v59
	v_rcp_f32_e32 v60, v60
	ds_write_b16 v79, v12 offset:96
	v_mov_b32_dpp v108, v95 quad_perm:[1,0,3,2] row_mask:0xf bank_mask:0xf
	v_max_f32_e32 v108, v108, v108
	v_max_f32_e32 v95, v95, v108
	v_mov_b32_e32 v108, 0
	v_mul_f32_e32 v14, v22, v60
; __device__ __forceinline__ unsigned f2bf(float f) { return pk2(f, f) & 0xffffu; }
; __device__ __forceinline__ float row16_sum(float v) { v += dpp_perm<0xB1, 0xF>(v); v += dpp_perm<0x4E, 0xF>(v); v += dpp_perm<0x141, 0xF>(v); v += dpp_perm<0x140, 0xF>(v); return v; }
; __device__ __forceinline__ float row16_max(float v) { v = fmaxf(v, dpp_perm<0xB1, 0xF>(v)); v = fmaxf(v, dpp_perm<0x4E, 0xF>(v)); v = fmaxf(v, dpp_perm<0x141, 0xF>(v)); v = fmaxf(v, dpp_perm<0x140, 0xF>(v)); return v; }
; __device__ __forceinline__ void attn_unit(const AtArgs& A, unsigned char* lds, int unit, int tid, int wave, int lane) {
;     ...
;         float m4[4], s4[4];
; #pragma unroll
;         for (int r = 0; r < 4; ++r) {
;             float m = sc[0][r];
; #pragma unroll
;             for (int kt = 1; kt < 9; ++kt) m = fmaxf(m, sc[kt][r]);
;             m = row16_max(m);
;             m4[r] = fmaxf(m, sink);
;             float s = 0.f;
; #pragma unroll
;             for (int kt = 0; kt < 9; ++kt) { const float e = __expf(sc[kt][r] - m4[r]); sc[kt][r] = e; s += e; }
;             s = row16_sum(s);
;             s4[r] = __builtin_amdgcn_rcpf(s + __expf(sink - m4[r]));
;         }
; #pragma unroll
;         for (int kt = 0; kt < 9; ++kt)
; #pragma unroll
;             for (int r = 0; r < 4; ++r) PS[(fq * 4 + r) * PST + kt * 16 + fr] = (bf16)f2bf(sc[kt][r] * s4[r]);
	v_mul_f32_e32 v10, v97, v60
	v_mov_b32_dpp v108, v95 quad_perm:[2,3,0,1] row_mask:0xf bank_mask:0xf
	v_max_f32_e32 v108, v108, v108
	v_max_f32_e32 v95, v95, v108
	v_mov_b32_e32 v108, 0
	v_cvt_pk_bf16_f32 v14, v14, s0
	v_cvt_pk_bf16_f32 v10, v10, s0
	v_mov_b32_dpp v108, v95 row_half_mirror row_mask:0xf bank_mask:0xf
	v_max_f32_e32 v108, v108, v108
	v_max_f32_e32 v95, v95, v108
	v_mov_b32_e32 v108, 0
	ds_write_b16 v79, v14 offset:336
	ds_write_b16 v79, v10 offset:464
	v_mov_b32_dpp v108, v95 row_mirror row_mask:0xf bank_mask:0xf
	v_max3_f32 v95, v95, v108, v38
	v_mul_f32_e32 v146, 0xbfb8aa3b, v95
	v_fmamk_f32 v18, v18, 0x3fb8aa3b, v146
	s_nop 0
	v_fmamk_f32 v20, v20, 0x3fb8aa3b, v146
	v_exp_f32_e32 v18, v18
	s_nop 0
	v_fmamk_f32 v23, v23, 0x3fb8aa3b, v146
	v_exp_f32_e32 v20, v20
	s_nop 0
	v_fmamk_f32 v27, v27, 0x3fb8aa3b, v146
	v_exp_f32_e32 v23, v23
	s_nop 0
	v_fmamk_f32 v57, v57, 0x3fb8aa3b, v146
	v_exp_f32_e32 v27, v27
	s_nop 0
	v_fmamk_f32 v98, v98, 0x3fb8aa3b, v146
	v_add_f32_e32 v108, 0, v18
	v_exp_f32_e32 v57, v57
	s_nop 0
	v_fmamk_f32 v102, v102, 0x3fb8aa3b, v146
	v_add_f32_e32 v108, v20, v108
	v_exp_f32_e32 v98, v98
	s_nop 0
	v_fmamk_f32 v109, v123, 0x3fb8aa3b, v146
	v_add_f32_e32 v108, v23, v108
	v_exp_f32_e32 v102, v102
	s_nop 0
	v_fmamk_f32 v59, v59, 0x3fb8aa3b, v146
	v_add_f32_e32 v108, v27, v108
	v_exp_f32_e32 v109, v109
	s_nop 0
	v_add_f32_e32 v108, v57, v108
	v_exp_f32_e32 v59, v59
	v_add_f32_e32 v108, v98, v108
	v_add_f32_e32 v108, v102, v108
	v_add_f32_e32 v108, v109, v108
	v_fmamk_f32 v95, v38, 0x3fb8aa3b, v146
	v_add_f32_e32 v108, v59, v108
	s_nop 0
	v_exp_f32_e32 v95, v95
	v_add_f32_dpp v108, v108, v108 quad_perm:[1,0,3,2] row_mask:0xf bank_mask:0xf bound_ctrl:1
	v_mul_f32_e32 v12, v96, v60
	ds_write_b16 v79, v9 offset:224
	v_add_f32_dpp v108, v108, v108 quad_perm:[2,3,0,1] row_mask:0xf bank_mask:0xf bound_ctrl:1
	v_mul_f32_e32 v9, v103, v60
	ds_write_b16 v79, v8 offset:256
	v_add_f32_dpp v108, v108, v108 row_half_mirror row_mask:0xf bank_mask:0xf bound_ctrl:1
	v_mul_f32_e32 v8, v58, v60
	v_cvt_pk_bf16_f32 v12, v12, s0
	v_add_f32_dpp v108, v108, v108 row_mirror row_mask:0xf bank_mask:0xf bound_ctrl:1
	v_add_f32_e32 v95, v95, v108
	v_max3_f32 v108, v16, v17, v19
	v_max3_f32 v108, v108, v21, v25
	v_max3_f32 v108, v108, v28, v61
	v_max3_f32 v108, v108, v99, v31
	v_rcp_f32_e32 v95, v95
	v_cvt_pk_bf16_f32 v9, v9, s0
	v_mov_b32_dpp v110, v108 quad_perm:[1,0,3,2] row_mask:0xf bank_mask:0xf
	v_max_f32_e32 v110, v110, v110
	v_max_f32_e32 v108, v108, v110
	v_mov_b32_e32 v110, 0
	v_mul_f32_e32 v14, v18, v95
	v_mul_f32_e32 v10, v57, v95
	v_mov_b32_dpp v110, v108 quad_perm:[2,3,0,1] row_mask:0xf bank_mask:0xf
	v_max_f32_e32 v110, v110, v110
	v_max_f32_e32 v108, v108, v110
	v_mov_b32_e32 v110, 0
	v_cvt_pk_bf16_f32 v14, v14, s0
	v_cvt_pk_bf16_f32 v10, v10, s0
	v_mov_b32_dpp v110, v108 row_half_mirror row_mask:0xf bank_mask:0xf
	v_max_f32_e32 v110, v110, v110
	v_max_f32_e32 v108, v108, v110
	v_mov_b32_e32 v110, 0
	ds_write_b16 v79, v14 offset:672
	ds_write_b16 v79, v10 offset:800
	v_mov_b32_dpp v110, v108 row_mirror row_mask:0xf bank_mask:0xf
	v_max3_f32 v108, v108, v110, v38
	v_mul_f32_e32 v147, 0xbfb8aa3b, v108
	v_fmamk_f32 v16, v16, 0x3fb8aa3b, v147
	s_nop 0
	v_fmamk_f32 v17, v17, 0x3fb8aa3b, v147
	v_exp_f32_e32 v16, v16
	s_nop 0
	v_fmamk_f32 v19, v19, 0x3fb8aa3b, v147
	v_exp_f32_e32 v17, v17
	s_nop 0
	v_fmamk_f32 v21, v21, 0x3fb8aa3b, v147
	v_exp_f32_e32 v19, v19
	s_nop 0
	v_fmamk_f32 v25, v25, 0x3fb8aa3b, v147
	v_exp_f32_e32 v21, v21
	s_nop 0
	v_fmamk_f32 v28, v28, 0x3fb8aa3b, v147
	v_add_f32_e32 v110, 0, v16
	v_exp_f32_e32 v25, v25
	s_nop 0
	v_fmamk_f32 v61, v61, 0x3fb8aa3b, v147
	v_add_f32_e32 v110, v17, v110
	v_exp_f32_e32 v28, v28
	s_nop 0
	v_fmamk_f32 v99, v99, 0x3fb8aa3b, v147
	v_add_f32_e32 v110, v19, v110
	v_exp_f32_e32 v61, v61
	s_nop 0
	v_fmamk_f32 v31, v31, 0x3fb8aa3b, v147
	v_add_f32_e32 v110, v21, v110
	v_exp_f32_e32 v99, v99
	s_nop 0
	v_add_f32_e32 v110, v25, v110
	v_exp_f32_e32 v31, v31
	v_add_f32_e32 v110, v28, v110
	v_add_f32_e32 v110, v61, v110
	v_add_f32_e32 v110, v99, v110
	v_fmamk_f32 v108, v38, 0x3fb8aa3b, v147
	v_add_f32_e32 v110, v31, v110
	s_nop 0
	v_exp_f32_e32 v108, v108
	v_add_f32_dpp v110, v110, v110 quad_perm:[1,0,3,2] row_mask:0xf bank_mask:0xf bound_ctrl:1
	v_cvt_pk_bf16_f32 v8, v8, s0
	ds_write_b16 v79, v12 offset:432
	v_add_f32_dpp v110, v110, v110 quad_perm:[2,3,0,1] row_mask:0xf bank_mask:0xf bound_ctrl:1
	v_mul_f32_e32 v12, v27, v95
	ds_write_b16 v79, v9 offset:560
	v_add_f32_dpp v110, v110, v110 row_half_mirror row_mask:0xf bank_mask:0xf bound_ctrl:1
	v_mul_f32_e32 v9, v109, v95
	ds_write_b16 v79, v8 offset:592
	v_add_f32_dpp v110, v110, v110 row_mirror row_mask:0xf bank_mask:0xf bound_ctrl:1
	v_add_f32_e32 v108, v108, v110
	v_rcp_f32_e32 v108, v108
	v_mul_f32_e32 v8, v59, v95
	v_cvt_pk_bf16_f32 v12, v12, s0
	v_cvt_pk_bf16_f32 v9, v9, s0
	v_mul_f32_e32 v14, v16, v108
	v_mul_f32_e32 v10, v25, v108
	v_cvt_pk_bf16_f32 v14, v14, s0
	v_cvt_pk_bf16_f32 v10, v10, s0
	ds_write_b16 v79, v14 offset:1008
	v_mul_f32_e32 v14, v29, v30
	ds_write_b16 v79, v10 offset:1136
	v_mul_f32_e32 v10, v13, v30
	v_cvt_pk_bf16_f32 v14, v14, s0
	v_cvt_pk_bf16_f32 v10, v10, s0
	ds_write_b16 v79, v14 offset:32
	v_mul_f32_e32 v14, v26, v60
	ds_write_b16 v79, v10 offset:160
	v_mul_f32_e32 v10, v100, v60
	v_cvt_pk_bf16_f32 v14, v14, s0
	v_cvt_pk_bf16_f32 v10, v10, s0
	ds_write_b16 v79, v14 offset:368
	v_mul_f32_e32 v14, v20, v95
	ds_write_b16 v79, v10 offset:496
	v_mul_f32_e32 v10, v98, v95
	v_cvt_pk_bf16_f32 v14, v14, s0
	v_cvt_pk_bf16_f32 v10, v10, s0
	ds_write_b16 v79, v14 offset:704
	v_mul_f32_e32 v14, v17, v108
; __device__ __forceinline__ unsigned f2bf(float f) { return pk2(f, f) & 0xffffu; }
; #define LDS_WAIT() asm volatile("s_waitcnt lgkmcnt(0)" ::: "memory")
; __device__ __forceinline__ void attn_unit(const AtArgs& A, unsigned char* lds, int unit, int tid, int wave, int lane) {
;     ...
; #pragma unroll
;         for (int kt = 0; kt < 9; ++kt)
; #pragma unroll
;             for (int r = 0; r < 4; ++r) PS[(fq * 4 + r) * PST + kt * 16 + fr] = (bf16)f2bf(sc[kt][r] * s4[r]);
; #pragma unroll
;         for (int r = 0; r < 4; ++r) PS[(fq * 4 + r) * PST + 144 + fr] = 0;
;         LDS_WAIT();
;         f32x4 o[4];
; #pragma unroll
;         for (int dt = 0; dt < 4; ++dt) o[dt] = (f32x4){0.f, 0.f, 0.f, 0.f};
; #pragma unroll
;         for (int ks = 0; ks < 5; ++ks) {
;             const bf16x8 pa = *(const bf16x8*)(PS + fr * PST + ks * 32 + fq * 8);
; #pragma unroll
;             for (int dt = 0; dt < 4; ++dt) {
;                 const bf16x8 vb = *(const bf16x8*)(VT + (dt * 16 + fr) * VST + (((((q0 + ks * 32) >> 3) + fq) ^ ((dt * 2 + (fr >> 3)) & 7)) << 3));
;                 o[dt] = __builtin_amdgcn_mfma_f32_16x16x32_bf16(pa, vb, o[dt], 0, 0, 0);
;             }
;         }
	ds_write_b16 v79, v10 offset:832
	v_mul_f32_e32 v10, v28, v108
	v_cvt_pk_bf16_f32 v14, v14, s0
	v_cvt_pk_bf16_f32 v10, v10, s0
	ds_write_b16 v79, v14 offset:1040
	v_mul_f32_e32 v14, v15, v30
	ds_write_b16 v79, v10 offset:1168
	v_mul_f32_e32 v10, v11, v30
	v_cvt_pk_bf16_f32 v14, v14, s0
	v_cvt_pk_bf16_f32 v10, v10, s0
	ds_write_b16 v79, v14 offset:64
	v_mul_f32_e32 v14, v56, v60
	ds_write_b16 v79, v10 offset:192
	v_mul_f32_e32 v10, v101, v60
	v_cvt_pk_bf16_f32 v14, v14, s0
	v_cvt_pk_bf16_f32 v10, v10, s0
	ds_write_b16 v79, v14 offset:400
	v_mul_f32_e32 v14, v23, v95
	ds_write_b16 v79, v10 offset:528
	v_mul_f32_e32 v10, v102, v95
	v_cvt_pk_bf16_f32 v14, v14, s0
	v_cvt_pk_bf16_f32 v10, v10, s0
	v_cvt_pk_bf16_f32 v8, v8, s0
	ds_write_b16 v79, v14 offset:736
	v_mul_f32_e32 v14, v19, v108
	ds_write_b16 v79, v12 offset:768
	v_mul_f32_e32 v12, v21, v108
	ds_write_b16 v79, v10 offset:864
	v_mul_f32_e32 v10, v61, v108
	ds_write_b16 v79, v9 offset:896
	v_mul_f32_e32 v9, v99, v108
	ds_write_b16 v79, v8 offset:928
	v_mul_f32_e32 v8, v31, v108
	v_cvt_pk_bf16_f32 v14, v14, s0
	v_cvt_pk_bf16_f32 v12, v12, s0
	v_cvt_pk_bf16_f32 v10, v10, s0
	v_cvt_pk_bf16_f32 v9, v9, s0
	v_cvt_pk_bf16_f32 v8, v8, s0
	ds_write_b16 v79, v14 offset:1072
	ds_write_b16 v79, v12 offset:1104
	ds_write_b16 v79, v10 offset:1200
	ds_write_b16 v79, v9 offset:1232
	ds_write_b16 v79, v8 offset:1264
	ds_write_b16 v79, v39 offset:288
	ds_write_b16 v79, v39 offset:624
	ds_write_b16 v79, v39 offset:960
	ds_write_b16 v79, v39 offset:1296
	s_waitcnt lgkmcnt(0)
	ds_read_b128 v[8:11], v77
	v_add_u32_e32 v25, -8, v94
	v_xor_b32_e32 v12, v25, v78
	v_xor_b32_e32 v16, v25, v82
	v_xor_b32_e32 v20, v25, v83
	v_xor_b32_e32 v25, v25, v84
	v_lshl_add_u32 v12, v12, 4, v80
	v_lshl_add_u32 v16, v16, 4, v80
	v_lshl_add_u32 v20, v20, 4, v80
	v_lshl_add_u32 v25, v25, 4, v81
	ds_read_b128 v[12:15], v12 offset:36864
	ds_read_b128 v[16:19], v16 offset:47872
	ds_read_b128 v[20:23], v20 offset:58880
	ds_read_b128 v[26:29], v25 offset:33024
	v_add_u32_e32 v25, -4, v94
	v_xor_b32_e32 v30, v25, v78
	v_lshl_add_u32 v30, v30, 4, v80
	ds_read_b128 v[56:59], v30 offset:36864
	s_waitcnt lgkmcnt(4)
	v_mfma_f32_16x16x32_bf16 v[12:15], v[8:11], v[12:15], 0
	v_xor_b32_e32 v30, v25, v82
	v_lshl_add_u32 v30, v30, 4, v80
	v_mov_b32_e32 v95, v24
	s_waitcnt lgkmcnt(3)
	v_mfma_f32_16x16x32_bf16 v[16:19], v[8:11], v[16:19], 0
	s_waitcnt lgkmcnt(2)
	v_mfma_f32_16x16x32_bf16 v[20:23], v[8:11], v[20:23], 0
	s_waitcnt lgkmcnt(1)
	v_mfma_f32_16x16x32_bf16 v[8:11], v[8:11], v[26:29], 0
	ds_read_b128 v[26:29], v77 offset:64
	s_waitcnt lgkmcnt(0)
	v_mfma_f32_16x16x32_bf16 v[12:15], v[26:29], v[56:59], v[12:15]
	ds_read_b128 v[56:59], v30 offset:47872
	v_xor_b32_e32 v30, v25, v83
	v_lshl_add_u32 v30, v30, 4, v80
	s_waitcnt lgkmcnt(0)
	v_mfma_f32_16x16x32_bf16 v[16:19], v[26:29], v[56:59], v[16:19]
	ds_read_b128 v[56:59], v30 offset:58880
	v_xor_b32_e32 v25, v25, v84
	v_lshl_add_u32 v25, v25, 4, v81
	s_waitcnt lgkmcnt(0)
	v_mfma_f32_16x16x32_bf16 v[20:23], v[26:29], v[56:59], v[20:23]
	ds_read_b128 v[56:59], v25 offset:33024
	v_xor_b32_e32 v25, v94, v78
	v_lshl_add_u32 v25, v25, 4, v80
	s_waitcnt lgkmcnt(0)
	v_mfma_f32_16x16x32_bf16 v[8:11], v[26:29], v[56:59], v[8:11]
	ds_read_b128 v[26:29], v77 offset:128
	ds_read_b128 v[56:59], v25 offset:36864
	v_xor_b32_e32 v25, v94, v82
	v_lshl_add_u32 v25, v25, 4, v80
	s_waitcnt lgkmcnt(0)
	v_mfma_f32_16x16x32_bf16 v[12:15], v[26:29], v[56:59], v[12:15]
	ds_read_b128 v[56:59], v25 offset:47872
	v_xor_b32_e32 v25, v94, v83
	v_lshl_add_u32 v25, v25, 4, v80
	s_waitcnt lgkmcnt(0)
	v_mfma_f32_16x16x32_bf16 v[16:19], v[26:29], v[56:59], v[16:19]
	ds_read_b128 v[56:59], v25 offset:58880
	v_add_u32_e32 v25, 4, v94
	s_waitcnt lgkmcnt(0)
; __device__ __forceinline__ unsigned f2bf(float f) { return pk2(f, f) & 0xffffu; }
; #define LDS_WAIT() asm volatile("s_waitcnt lgkmcnt(0)" ::: "memory")
; __device__ __forceinline__ void attn_unit(const AtArgs& A, unsigned char* lds, int unit, int tid, int wave, int lane) {
;     ...
;         for (int ks = 0; ks < 5; ++ks) {
;             const bf16x8 pa = *(const bf16x8*)(PS + fr * PST + ks * 32 + fq * 8);
; #pragma unroll
;             for (int dt = 0; dt < 4; ++dt) {
;                 const bf16x8 vb = *(const bf16x8*)(VT + (dt * 16 + fr) * VST + (((((q0 + ks * 32) >> 3) + fq) ^ ((dt * 2 + (fr >> 3)) & 7)) << 3));
;                 o[dt] = __builtin_amdgcn_mfma_f32_16x16x32_bf16(pa, vb, o[dt], 0, 0, 0);
;             }
;         }
;         LDS_WAIT();
; #pragma unroll
;         for (int r = 0; r < 4; ++r)
; #pragma unroll
;             for (int dt = 0; dt < 4; ++dt) PS[(fq * 4 + r) * PST + dt * 16 + fr] = (bf16)f2bf(o[dt][r]);
;         LDS_WAIT();
; #pragma unroll
;         for (int j = 0; j < 2; ++j) {
;             const int tk = (lane >> 3) + 8 * j, c16 = lane & 7;
;             const size_t t = (size_t)b * SEQ + nb * 128 + q0 + tk;
;             *(u32x4*)(YB + t * 512 + hq * 64 + c16 * 8) = *(const u32x4*)(PS + tk * PST + c16 * 8);
;         }
;         LDS_WAIT();
;     }
	v_mfma_f32_16x16x32_bf16 v[56:59], v[26:29], v[56:59], v[20:23]
	s_nop 2
	v_xor_b32_e32 v20, v94, v84
	v_lshl_add_u32 v20, v20, 4, v81
	ds_read_b128 v[20:23], v20 offset:33024
	s_waitcnt lgkmcnt(0)
	v_mfma_f32_16x16x32_bf16 v[8:11], v[26:29], v[20:23], v[8:11]
	ds_read_b128 v[26:29], v77 offset:192
	v_xor_b32_e32 v20, v25, v78
	v_lshl_add_u32 v20, v20, 4, v80
	ds_read_b128 v[20:23], v20 offset:36864
	s_waitcnt lgkmcnt(0)
	v_mfma_f32_16x16x32_bf16 v[20:23], v[26:29], v[20:23], v[12:15]
	s_nop 2
	v_xor_b32_e32 v12, v25, v82
	v_lshl_add_u32 v12, v12, 4, v80
	ds_read_b128 v[12:15], v12 offset:47872
	s_waitcnt lgkmcnt(0)
	v_mfma_f32_16x16x32_bf16 v[16:19], v[26:29], v[12:15], v[16:19]
	v_xor_b32_e32 v12, v25, v83
	v_lshl_add_u32 v12, v12, 4, v80
	ds_read_b128 v[12:15], v12 offset:58880
	v_xor_b32_e32 v25, v25, v84
	v_lshl_add_u32 v25, v25, 4, v81
	s_waitcnt lgkmcnt(0)
	v_mfma_f32_16x16x32_bf16 v[12:15], v[26:29], v[12:15], v[56:59]
	s_nop 2
	ds_read_b128 v[56:59], v25 offset:33024
	v_add_u32_e32 v25, 8, v94
	s_waitcnt lgkmcnt(0)
	v_mfma_f32_16x16x32_bf16 v[8:11], v[26:29], v[56:59], v[8:11]
	ds_read_b128 v[26:29], v77 offset:256
	v_xor_b32_e32 v30, v25, v78
	v_lshl_add_u32 v30, v30, 4, v80
	ds_read_b128 v[56:59], v30 offset:36864
	v_xor_b32_e32 v30, v25, v82
	v_lshl_add_u32 v30, v30, 4, v80
	s_waitcnt lgkmcnt(0)
	v_mfma_f32_16x16x32_bf16 v[20:23], v[26:29], v[56:59], v[20:23]
	ds_read_b128 v[56:59], v30 offset:47872
	v_xor_b32_e32 v30, v25, v83
	v_lshl_add_u32 v30, v30, 4, v80
	s_waitcnt lgkmcnt(0)
	v_mfma_f32_16x16x32_bf16 v[16:19], v[26:29], v[56:59], v[16:19]
	ds_read_b128 v[56:59], v30 offset:58880
	v_xor_b32_e32 v25, v25, v84
	v_lshl_add_u32 v25, v25, 4, v81
	s_waitcnt lgkmcnt(0)
	v_mfma_f32_16x16x32_bf16 v[12:15], v[26:29], v[56:59], v[12:15]
	ds_read_b128 v[56:59], v25 offset:33024
	s_waitcnt lgkmcnt(0)
	v_cvt_pk_bf16_f32 v20, v20, s0
	s_waitcnt lgkmcnt(0)
	v_mfma_f32_16x16x32_bf16 v[8:11], v[26:29], v[56:59], v[8:11]
	v_cvt_pk_bf16_f32 v16, v16, s0
	s_nop 2
	v_cvt_pk_bf16_f32 v12, v12, s0
	ds_write_b16 v79, v20
	s_nop 1
	v_cvt_pk_bf16_f32 v8, v8, s0
	ds_write_b16 v79, v8 offset:96
	v_cvt_pk_bf16_f32 v8, v21, s0
	ds_write_b16 v79, v8 offset:336
	v_cvt_pk_bf16_f32 v8, v17, s0
	ds_write_b16 v79, v8 offset:368
	v_cvt_pk_bf16_f32 v8, v13, s0
	ds_write_b16 v79, v8 offset:400
	v_cvt_pk_bf16_f32 v8, v9, s0
	ds_write_b16 v79, v8 offset:432
	v_cvt_pk_bf16_f32 v8, v22, s0
	ds_write_b16 v79, v8 offset:672
	v_cvt_pk_bf16_f32 v8, v18, s0
	ds_write_b16 v79, v8 offset:704
	v_cvt_pk_bf16_f32 v8, v14, s0
	ds_write_b16 v79, v8 offset:736
	v_cvt_pk_bf16_f32 v8, v10, s0
	ds_write_b16 v79, v8 offset:768
	v_cvt_pk_bf16_f32 v8, v23, s0
	ds_write_b16 v79, v8 offset:1008
	v_cvt_pk_bf16_f32 v8, v19, s0
	ds_write_b16 v79, v8 offset:1040
	v_cvt_pk_bf16_f32 v8, v15, s0
	ds_write_b16 v79, v8 offset:1072
	v_cvt_pk_bf16_f32 v8, v11, s0
	ds_write_b16 v79, v16 offset:32
	ds_write_b16 v79, v12 offset:64
	ds_write_b16 v79, v8 offset:1104
	s_waitcnt lgkmcnt(0)
	ds_read_b128 v[8:11], v92
	v_lshl_add_u64 v[12:13], v[52:53], 0, s[20:21]
	s_mov_b32 s0, 0x1d800000
	v_add_co_u32_e32 v14, vcc, s0, v12
	s_mov_b32 s0, 0x1d802000
	s_nop 0
	v_addc_co_u32_e32 v15, vcc, 0, v13, vcc
	s_waitcnt lgkmcnt(0)
	global_store_dwordx4 v[14:15], v[8:11], off
	ds_read_b128 v[8:11], v92 offset:2688
	v_add_co_u32_e32 v12, vcc, s0, v12
	s_add_u32 s20, s20, 0x4000
	s_nop 0
	v_addc_co_u32_e32 v13, vcc, 0, v13, vcc
	s_waitcnt lgkmcnt(0)
	global_store_dwordx4 v[12:13], v[8:11], off
	s_waitcnt lgkmcnt(0)
	s_addc_u32 s21, s21, 0
	s_mov_b64 s[0:1], 0x400
	v_mov_b64_e32 v[14:15], v[6:7]
	v_mov_b64_e32 v[10:11], v[2:3]
	v_add_u32_e32 v94, 2, v94
	v_lshl_add_u64 v[54:55], v[54:55], 0, s[0:1]
	s_cmp_lg_u32 s2, 64
	v_mov_b64_e32 v[12:13], v[4:5]
	v_mov_b64_e32 v[8:9], v[0:1]
	s_cbranch_scc0 .LBB0_492
